# P0 hb-init: x/meta row loads marked nt (read once, do not displace the freshly written weights/hb from the caches)
# speedup vs baseline: 1.0094x; 1.0041x over previous
; DI unsigned pk2(float a, float b) { f32x2 v = {a, b}; bf16v2 r = __builtin_convertvector(v, bf16v2); return __builtin_bit_cast(unsigned, r); }
; DI void phase_p0(const Params& p, LAS unsigned char* lds, int gw, int NGW, int wave, int lane) {
;     ...
;     for (int r0 = gw; r0 < LTOK; r0 += 2 * NGW) {
;         f32x4 v[2][8];
; #pragma unroll
;         for (int q = 0; q < 2; ++q) { const int r = r0 + q * NGW < LTOK ? r0 + q * NGW : r0;
;             const f32x4* src = (const f32x4*)(r < SEQ ? p.x + (size_t)r * D : p.meta + (size_t)(r - SEQ) * D) + 2 * lane;
; #pragma unroll
;             for (int j = 0; j < 4; ++j) { v[q][2 * j] = src[128 * j]; v[q][2 * j + 1] = src[128 * j + 1]; } }
; #pragma unroll
;         for (int q = 0; q < 2; ++q) { const int r = r0 + q * NGW; if (r >= LTOK) break;
;             u32x4* ob = (u32x4*)(hb + (size_t)r * D) + lane;
; #pragma unroll
;             for (int j = 0; j < 4; ++j) { const f32x4 a0 = v[q][2 * j], a1 = v[q][2 * j + 1]; u32x4 w; w.x = pk2(a0[0], a0[1]); w.y = pk2(a0[2], a0[3]); w.z = pk2(a1[0], a1[1]); w.w = pk2(a1[2], a1[3]); ob[64 * j] = w; } }
;     }
.LBB0_35:
	s_add_i32 s12, s4, 0xffffc000
	s_ashr_i32 s5, s4, 31
	s_cmpk_lt_i32 s4, 0x4000
	s_cselect_b32 s13, s5, 0
	s_cselect_b32 s12, s4, s12
	s_waitcnt lgkmcnt(0)
	s_cselect_b32 s15, s73, s75
	s_cselect_b32 s14, s72, s74
	s_lshl_b64 s[12:13], s[12:13], 13
	s_add_u32 s14, s14, s12
	s_addc_u32 s15, s15, s13
	s_add_i32 s12, s4, s0
	s_cmpk_lt_i32 s12, 0x4010
	s_cselect_b32 s13, s12, s4
	global_load_dwordx4 v[40:43], v36, s[14:15] nt
	global_load_dwordx4 v[44:47], v36, s[14:15] offset:16 nt
	s_waitcnt vmcnt(11)
	v_lshl_add_u64 v[2:3], s[14:15], 0, v[36:37]
	global_load_dwordx4 v[48:51], v36, s[14:15] offset:2064 nt
	global_load_dwordx4 v[52:55], v36, s[14:15] offset:2048 nt
	s_ashr_i32 s14, s13, 31
	s_add_i32 s16, s13, 0xffffc000
	s_cmpk_lt_i32 s13, 0x4000
	s_cselect_b32 s15, s14, 0
	s_cselect_b32 s14, s13, s16
	s_cselect_b32 s13, s73, s75
	s_cselect_b32 s16, s72, s74
	s_lshl_b64 s[14:15], s[14:15], 13
	s_waitcnt vmcnt(8)
	v_add_co_u32_e32 v6, vcc, s1, v2
	s_add_u32 s14, s16, s14
	s_nop 0
	v_addc_co_u32_e32 v7, vcc, 0, v3, vcc
	s_addc_u32 s15, s13, s15
	v_lshl_add_u64 v[4:5], v[2:3], 0, s[8:9]
	v_lshl_add_u64 v[2:3], v[2:3], 0, s[10:11]
	global_load_dwordx4 v[56:59], v[6:7], off nt
	global_load_dwordx4 v[60:63], v[4:5], off offset:16 nt
	global_load_dwordx4 v[64:67], v[6:7], off offset:2048 nt
	global_load_dwordx4 v[68:71], v[2:3], off offset:16 nt
	v_lshl_add_u64 v[6:7], s[14:15], 0, v[36:37]
	v_add_co_u32_e32 v74, vcc, s1, v6
	global_load_dwordx4 v[26:29], v36, s[14:15] offset:16 nt
	global_load_dwordx4 v[30:33], v36, s[14:15] nt
	global_load_dwordx4 v[2:5], v36, s[14:15] offset:2064 nt
	global_load_dwordx4 v[14:17], v36, s[14:15] offset:2048 nt
	v_addc_co_u32_e32 v75, vcc, 0, v7, vcc
	v_lshl_add_u64 v[72:73], v[6:7], 0, s[8:9]
	v_lshl_add_u64 v[76:77], v[6:7], 0, s[10:11]
	global_load_dwordx4 v[22:25], v[74:75], off nt
	global_load_dwordx4 v[18:21], v[72:73], off offset:16 nt
	global_load_dwordx4 v[10:13], v[74:75], off offset:2048 nt
	global_load_dwordx4 v[6:9], v[76:77], off offset:16 nt
	s_lshl_b64 s[4:5], s[4:5], 12
	v_lshl_add_u64 v[72:73], v[38:39], 0, s[4:5]
	s_cmpk_gt_i32 s12, 0x400f
	s_waitcnt vmcnt(15)
	v_cvt_pk_bf16_f32 v40, v40, v41
	v_cvt_pk_bf16_f32 v41, v42, v43
	s_waitcnt vmcnt(14)
	v_cvt_pk_bf16_f32 v42, v44, v45
	v_cvt_pk_bf16_f32 v43, v46, v47
	s_waitcnt vmcnt(12)
	v_cvt_pk_bf16_f32 v44, v52, v53
	v_cvt_pk_bf16_f32 v45, v54, v55
	v_cvt_pk_bf16_f32 v46, v48, v49
	v_cvt_pk_bf16_f32 v47, v50, v51
	global_store_dwordx4 v[72:73], v[40:43], off
	global_store_dwordx4 v[72:73], v[44:47], off offset:1024
	s_waitcnt vmcnt(13)
	v_cvt_pk_bf16_f32 v40, v56, v57
	v_cvt_pk_bf16_f32 v41, v58, v59
	s_waitcnt vmcnt(12)
	v_cvt_pk_bf16_f32 v42, v60, v61
	v_cvt_pk_bf16_f32 v43, v62, v63
	global_store_dwordx4 v[72:73], v[40:43], off offset:2048
	s_waitcnt vmcnt(12)
	s_nop 0
	v_cvt_pk_bf16_f32 v40, v64, v65
	v_cvt_pk_bf16_f32 v41, v66, v67
	s_waitcnt vmcnt(11)
	v_cvt_pk_bf16_f32 v42, v68, v69
	v_cvt_pk_bf16_f32 v43, v70, v71
	global_store_dwordx4 v[72:73], v[40:43], off offset:3072
	s_cbranch_scc1 .LBB0_34
	s_ashr_i32 s13, s12, 31
	s_lshl_b64 s[4:5], s[12:13], 12
	v_lshl_add_u64 v[40:41], v[38:39], 0, s[4:5]
	s_waitcnt vmcnt(8)
	v_cvt_pk_bf16_f32 v14, v14, v15
	v_cvt_pk_bf16_f32 v15, v16, v17
	v_cvt_pk_bf16_f32 v16, v2, v3
	v_cvt_pk_bf16_f32 v17, v4, v5
	s_waitcnt vmcnt(7)
	v_cvt_pk_bf16_f32 v2, v22, v23
	v_cvt_pk_bf16_f32 v3, v24, v25
	s_waitcnt vmcnt(6)
	v_cvt_pk_bf16_f32 v4, v18, v19
	v_cvt_pk_bf16_f32 v5, v20, v21
	v_cvt_pk_bf16_f32 v30, v30, v31
	v_cvt_pk_bf16_f32 v31, v32, v33
	v_cvt_pk_bf16_f32 v32, v26, v27
	v_cvt_pk_bf16_f32 v33, v28, v29
	global_store_dwordx4 v[40:41], v[2:5], off offset:2048
	global_store_dwordx4 v[40:41], v[30:33], off
	global_store_dwordx4 v[40:41], v[14:17], off offset:1024
	s_waitcnt vmcnt(8)
	v_cvt_pk_bf16_f32 v2, v10, v11
	v_cvt_pk_bf16_f32 v3, v12, v13
	s_waitcnt vmcnt(7)
	v_cvt_pk_bf16_f32 v4, v6, v7
	v_cvt_pk_bf16_f32 v5, v8, v9
	global_store_dwordx4 v[40:41], v[2:5], off offset:3072
	s_branch .LBB0_34
